# P1 rotary epilogue: cos/sin rows of 6 row groups in flight instead of one load per vmcnt(0)
# speedup vs baseline: 1.0102x; 1.0102x over previous
.LBB0_192:
	s_cmp_lt_i32 s58, 2
	s_cselect_b64 s[2:3], -1, 0
	v_cndmask_b32_e64 v144, v179, 1.0, s[2:3]
	v_ashrrev_i32_e32 v0, 31, v202
	v_mul_lo_u32 v203, s56, v0
	v_lshl_add_u64 v[170:171], v[170:171], 1, s[86:87]
	v_and_b32_e32 v0, s65, v202
	v_lshlrev_b32_e32 v0, 7, v0
	v_lshl_add_u64 v[132:133], v[162:163], 0, v[0:1]
	global_load_dwordx4 v[136:139], v[132:133], off
	v_lshl_add_u64 v[132:133], v[164:165], 0, v[0:1]
	global_load_dwordx4 v[140:143], v[132:133], off
	v_or_b32_e32 v145, 16, v202
	v_and_b32_e32 v0, s65, v145
	v_lshlrev_b32_e32 v0, 7, v0
	v_lshl_add_u64 v[132:133], v[162:163], 0, v[0:1]
	global_load_dwordx4 v[208:211], v[132:133], off
	v_lshl_add_u64 v[132:133], v[164:165], 0, v[0:1]
	global_load_dwordx4 v[216:219], v[132:133], off
	v_or_b32_e32 v145, 32, v202
	v_and_b32_e32 v0, s65, v145
	v_lshlrev_b32_e32 v0, 7, v0
	v_lshl_add_u64 v[132:133], v[162:163], 0, v[0:1]
	global_load_dwordx4 v[220:223], v[132:133], off
	v_lshl_add_u64 v[132:133], v[164:165], 0, v[0:1]
	global_load_dwordx4 v[224:227], v[132:133], off
	v_or_b32_e32 v145, 48, v202
	v_and_b32_e32 v0, s65, v145
	v_lshlrev_b32_e32 v0, 7, v0
	v_lshl_add_u64 v[132:133], v[162:163], 0, v[0:1]
	global_load_dwordx4 v[228:231], v[132:133], off
	v_lshl_add_u64 v[132:133], v[164:165], 0, v[0:1]
	global_load_dwordx4 v[232:235], v[132:133], off
	v_or_b32_e32 v145, 0x80, v202
	v_and_b32_e32 v0, s65, v145
	v_lshlrev_b32_e32 v0, 7, v0
	v_lshl_add_u64 v[132:133], v[162:163], 0, v[0:1]
	global_load_dwordx4 v[236:239], v[132:133], off
	v_lshl_add_u64 v[132:133], v[164:165], 0, v[0:1]
	global_load_dwordx4 v[240:243], v[132:133], off
	v_or_b32_e32 v145, 0x90, v202
	v_and_b32_e32 v0, s65, v145
	v_lshlrev_b32_e32 v0, 7, v0
	v_lshl_add_u64 v[132:133], v[162:163], 0, v[0:1]
	global_load_dwordx4 v[174:177], v[132:133], off
	v_lshl_add_u64 v[132:133], v[164:165], 0, v[0:1]
	global_load_dwordx4 v[204:207], v[132:133], off
	v_mul_lo_u32 v0, s57, v202
	v_mad_u64_u32 v[212:213], s[2:3], s56, v202, 0
	v_add3_u32 v213, v213, v203, v0
	v_lshlrev_b64 v[212:213], 1, v[212:213]
	s_waitcnt vmcnt(10)
	v_pk_mul_f32 v[136:137], v[144:145], v[136:137] op_sel_hi:[0,1]
	v_pk_mul_f32 v[138:139], v[144:145], v[138:139] op_sel_hi:[0,1]
	v_pk_mul_f32 v[140:141], v[144:145], v[140:141] op_sel_hi:[0,1]
	v_pk_mul_f32 v[142:143], v[144:145], v[142:143] op_sel_hi:[0,1]
	v_pk_mul_f32 v[130:131], v[122:123], v[140:141]
	v_pk_mul_f32 v[132:133], v[124:125], v[142:143]
	v_pk_fma_f32 v[130:131], v[126:127], v[136:137], v[130:131] neg_lo:[0,0,1] neg_hi:[0,0,1]
	v_pk_fma_f32 v[132:133], v[128:129], v[138:139], v[132:133] neg_lo:[0,0,1] neg_hi:[0,0,1]
	v_pk_mul_f32 v[126:127], v[126:127], v[140:141]
	v_pk_mul_f32 v[128:129], v[128:129], v[142:143]
	v_pk_fma_f32 v[122:123], v[122:123], v[136:137], v[126:127]
	v_pk_fma_f32 v[124:125], v[124:125], v[138:139], v[128:129]
	v_cvt_pk_bf16_f32 v126, v130, v131
	v_cvt_pk_bf16_f32 v127, v132, v133
	v_cvt_pk_bf16_f32 v128, v122, v123
	v_cvt_pk_bf16_f32 v129, v124, v125
	v_lshl_add_u64 v[132:133], v[170:171], 0, v[212:213]
	global_store_dwordx4 v[132:133], v[126:129], off
	v_pk_mul_f32 v[130:131], v[114:115], v[140:141]
	v_pk_mul_f32 v[132:133], v[116:117], v[142:143]
	v_pk_fma_f32 v[130:131], v[118:119], v[136:137], v[130:131] neg_lo:[0,0,1] neg_hi:[0,0,1]
	v_pk_fma_f32 v[132:133], v[120:121], v[138:139], v[132:133] neg_lo:[0,0,1] neg_hi:[0,0,1]
	v_pk_mul_f32 v[118:119], v[118:119], v[140:141]
	v_pk_mul_f32 v[120:121], v[120:121], v[142:143]
	v_pk_fma_f32 v[114:115], v[114:115], v[136:137], v[118:119]
	v_pk_fma_f32 v[116:117], v[116:117], v[138:139], v[120:121]
	v_cvt_pk_bf16_f32 v118, v130, v131
	v_cvt_pk_bf16_f32 v119, v132, v133
	v_cvt_pk_bf16_f32 v120, v114, v115
	v_cvt_pk_bf16_f32 v121, v116, v117
	v_lshl_add_u64 v[132:133], v[134:135], 0, v[212:213]
	global_store_dwordx4 v[132:133], v[118:121], off
	v_or_b32_e32 v145, 0xa0, v202
	v_and_b32_e32 v0, s65, v145
	v_lshlrev_b32_e32 v0, 7, v0
	v_lshl_add_u64 v[132:133], v[162:163], 0, v[0:1]
	global_load_dwordx4 v[136:139], v[132:133], off
	v_lshl_add_u64 v[132:133], v[164:165], 0, v[0:1]
	global_load_dwordx4 v[140:143], v[132:133], off
	v_or_b32_e32 v145, 0x10, v202
	v_mul_lo_u32 v0, s57, v145
	v_mad_u64_u32 v[212:213], s[2:3], s56, v145, 0
	v_add3_u32 v213, v213, v203, v0
	v_lshlrev_b64 v[212:213], 1, v[212:213]
	s_waitcnt vmcnt(12)
	v_pk_mul_f32 v[208:209], v[144:145], v[208:209] op_sel_hi:[0,1]
	v_pk_mul_f32 v[210:211], v[144:145], v[210:211] op_sel_hi:[0,1]
	v_pk_mul_f32 v[216:217], v[144:145], v[216:217] op_sel_hi:[0,1]
	v_pk_mul_f32 v[218:219], v[144:145], v[218:219] op_sel_hi:[0,1]
	v_pk_mul_f32 v[130:131], v[106:107], v[216:217]
	v_pk_mul_f32 v[132:133], v[108:109], v[218:219]
	v_pk_fma_f32 v[130:131], v[110:111], v[208:209], v[130:131] neg_lo:[0,0,1] neg_hi:[0,0,1]
	v_pk_fma_f32 v[132:133], v[112:113], v[210:211], v[132:133] neg_lo:[0,0,1] neg_hi:[0,0,1]
	v_pk_mul_f32 v[110:111], v[110:111], v[216:217]
	v_pk_mul_f32 v[112:113], v[112:113], v[218:219]
	v_pk_fma_f32 v[106:107], v[106:107], v[208:209], v[110:111]
	v_pk_fma_f32 v[108:109], v[108:109], v[210:211], v[112:113]
	v_cvt_pk_bf16_f32 v110, v130, v131
	v_cvt_pk_bf16_f32 v111, v132, v133
	v_cvt_pk_bf16_f32 v112, v106, v107
	v_cvt_pk_bf16_f32 v113, v108, v109
	v_lshl_add_u64 v[132:133], v[170:171], 0, v[212:213]
	global_store_dwordx4 v[132:133], v[110:113], off
	v_pk_mul_f32 v[130:131], v[98:99], v[216:217]
	v_pk_mul_f32 v[132:133], v[100:101], v[218:219]
	v_pk_fma_f32 v[130:131], v[102:103], v[208:209], v[130:131] neg_lo:[0,0,1] neg_hi:[0,0,1]
	v_pk_fma_f32 v[132:133], v[104:105], v[210:211], v[132:133] neg_lo:[0,0,1] neg_hi:[0,0,1]
	v_pk_mul_f32 v[102:103], v[102:103], v[216:217]
	v_pk_mul_f32 v[104:105], v[104:105], v[218:219]
	v_pk_fma_f32 v[98:99], v[98:99], v[208:209], v[102:103]
	v_pk_fma_f32 v[100:101], v[100:101], v[210:211], v[104:105]
	v_cvt_pk_bf16_f32 v102, v130, v131
	v_cvt_pk_bf16_f32 v103, v132, v133
	v_cvt_pk_bf16_f32 v104, v98, v99
	v_cvt_pk_bf16_f32 v105, v100, v101
	v_lshl_add_u64 v[132:133], v[134:135], 0, v[212:213]
	global_store_dwordx4 v[132:133], v[102:105], off
	v_or_b32_e32 v145, 0xb0, v202
	v_and_b32_e32 v0, s65, v145
	v_lshlrev_b32_e32 v0, 7, v0
	v_lshl_add_u64 v[132:133], v[162:163], 0, v[0:1]
	global_load_dwordx4 v[208:211], v[132:133], off
	v_lshl_add_u64 v[132:133], v[164:165], 0, v[0:1]
	global_load_dwordx4 v[216:219], v[132:133], off
	v_or_b32_e32 v145, 0x20, v202
	v_mul_lo_u32 v0, s57, v145
	v_mad_u64_u32 v[212:213], s[2:3], s56, v145, 0
	v_add3_u32 v213, v213, v203, v0
	v_lshlrev_b64 v[212:213], 1, v[212:213]
	s_waitcnt vmcnt(14)
	v_pk_mul_f32 v[220:221], v[144:145], v[220:221] op_sel_hi:[0,1]
	v_pk_mul_f32 v[222:223], v[144:145], v[222:223] op_sel_hi:[0,1]
	v_pk_mul_f32 v[224:225], v[144:145], v[224:225] op_sel_hi:[0,1]
	v_pk_mul_f32 v[226:227], v[144:145], v[226:227] op_sel_hi:[0,1]
	v_pk_mul_f32 v[130:131], v[90:91], v[224:225]
	v_pk_mul_f32 v[132:133], v[92:93], v[226:227]
	v_pk_fma_f32 v[130:131], v[94:95], v[220:221], v[130:131] neg_lo:[0,0,1] neg_hi:[0,0,1]
	v_pk_fma_f32 v[132:133], v[96:97], v[222:223], v[132:133] neg_lo:[0,0,1] neg_hi:[0,0,1]
	v_pk_mul_f32 v[94:95], v[94:95], v[224:225]
	v_pk_mul_f32 v[96:97], v[96:97], v[226:227]
	v_pk_fma_f32 v[90:91], v[90:91], v[220:221], v[94:95]
	v_pk_fma_f32 v[92:93], v[92:93], v[222:223], v[96:97]
	v_cvt_pk_bf16_f32 v94, v130, v131
	v_cvt_pk_bf16_f32 v95, v132, v133
	v_cvt_pk_bf16_f32 v96, v90, v91
	v_cvt_pk_bf16_f32 v97, v92, v93
	v_lshl_add_u64 v[132:133], v[170:171], 0, v[212:213]
	global_store_dwordx4 v[132:133], v[94:97], off
	v_pk_mul_f32 v[130:131], v[82:83], v[224:225]
	v_pk_mul_f32 v[132:133], v[84:85], v[226:227]
	v_pk_fma_f32 v[130:131], v[86:87], v[220:221], v[130:131] neg_lo:[0,0,1] neg_hi:[0,0,1]
	v_pk_fma_f32 v[132:133], v[88:89], v[222:223], v[132:133] neg_lo:[0,0,1] neg_hi:[0,0,1]
	v_pk_mul_f32 v[86:87], v[86:87], v[224:225]
	v_pk_mul_f32 v[88:89], v[88:89], v[226:227]
	v_pk_fma_f32 v[82:83], v[82:83], v[220:221], v[86:87]
	v_pk_fma_f32 v[84:85], v[84:85], v[222:223], v[88:89]
	v_cvt_pk_bf16_f32 v86, v130, v131
	v_cvt_pk_bf16_f32 v87, v132, v133
	v_cvt_pk_bf16_f32 v88, v82, v83
	v_cvt_pk_bf16_f32 v89, v84, v85
	v_lshl_add_u64 v[132:133], v[134:135], 0, v[212:213]
	global_store_dwordx4 v[132:133], v[86:89], off
	v_or_b32_e32 v145, 0x30, v202
	v_mul_lo_u32 v0, s57, v145
	v_mad_u64_u32 v[212:213], s[2:3], s56, v145, 0
	v_add3_u32 v213, v213, v203, v0
	v_lshlrev_b64 v[212:213], 1, v[212:213]
	s_waitcnt vmcnt(14)
	v_pk_mul_f32 v[228:229], v[144:145], v[228:229] op_sel_hi:[0,1]
	v_pk_mul_f32 v[230:231], v[144:145], v[230:231] op_sel_hi:[0,1]
	v_pk_mul_f32 v[232:233], v[144:145], v[232:233] op_sel_hi:[0,1]
	v_pk_mul_f32 v[234:235], v[144:145], v[234:235] op_sel_hi:[0,1]
	v_pk_mul_f32 v[130:131], v[74:75], v[232:233]
	v_pk_mul_f32 v[132:133], v[76:77], v[234:235]
	v_pk_fma_f32 v[130:131], v[78:79], v[228:229], v[130:131] neg_lo:[0,0,1] neg_hi:[0,0,1]
	v_pk_fma_f32 v[132:133], v[80:81], v[230:231], v[132:133] neg_lo:[0,0,1] neg_hi:[0,0,1]
	v_pk_mul_f32 v[78:79], v[78:79], v[232:233]
	v_pk_mul_f32 v[80:81], v[80:81], v[234:235]
	v_pk_fma_f32 v[74:75], v[74:75], v[228:229], v[78:79]
	v_pk_fma_f32 v[76:77], v[76:77], v[230:231], v[80:81]
	v_cvt_pk_bf16_f32 v78, v130, v131
	v_cvt_pk_bf16_f32 v79, v132, v133
	v_cvt_pk_bf16_f32 v80, v74, v75
	v_cvt_pk_bf16_f32 v81, v76, v77
	v_lshl_add_u64 v[132:133], v[170:171], 0, v[212:213]
	global_store_dwordx4 v[132:133], v[78:81], off
	v_pk_mul_f32 v[130:131], v[66:67], v[232:233]
	v_pk_mul_f32 v[132:133], v[68:69], v[234:235]
	v_pk_fma_f32 v[130:131], v[70:71], v[228:229], v[130:131] neg_lo:[0,0,1] neg_hi:[0,0,1]
	v_pk_fma_f32 v[132:133], v[72:73], v[230:231], v[132:133] neg_lo:[0,0,1] neg_hi:[0,0,1]
	v_pk_mul_f32 v[70:71], v[70:71], v[232:233]
	v_pk_mul_f32 v[72:73], v[72:73], v[234:235]
	v_pk_fma_f32 v[66:67], v[66:67], v[228:229], v[70:71]
	v_pk_fma_f32 v[68:69], v[68:69], v[230:231], v[72:73]
	v_cvt_pk_bf16_f32 v70, v130, v131
	v_cvt_pk_bf16_f32 v71, v132, v133
	v_cvt_pk_bf16_f32 v72, v66, v67
	v_cvt_pk_bf16_f32 v73, v68, v69
	v_lshl_add_u64 v[132:133], v[134:135], 0, v[212:213]
	global_store_dwordx4 v[132:133], v[70:73], off
	v_or_b32_e32 v145, 0x80, v202
	v_mul_lo_u32 v0, s57, v145
	v_mad_u64_u32 v[212:213], s[2:3], s56, v145, 0
	v_add3_u32 v213, v213, v203, v0
	v_lshlrev_b64 v[212:213], 1, v[212:213]
	s_waitcnt vmcnt(14)
	v_pk_mul_f32 v[236:237], v[144:145], v[236:237] op_sel_hi:[0,1]
	v_pk_mul_f32 v[238:239], v[144:145], v[238:239] op_sel_hi:[0,1]
	v_pk_mul_f32 v[240:241], v[144:145], v[240:241] op_sel_hi:[0,1]
	v_pk_mul_f32 v[242:243], v[144:145], v[242:243] op_sel_hi:[0,1]
	v_pk_mul_f32 v[130:131], v[58:59], v[240:241]
	v_pk_mul_f32 v[132:133], v[60:61], v[242:243]
	v_pk_fma_f32 v[130:131], v[62:63], v[236:237], v[130:131] neg_lo:[0,0,1] neg_hi:[0,0,1]
	v_pk_fma_f32 v[132:133], v[64:65], v[238:239], v[132:133] neg_lo:[0,0,1] neg_hi:[0,0,1]
	v_pk_mul_f32 v[62:63], v[62:63], v[240:241]
	v_pk_mul_f32 v[64:65], v[64:65], v[242:243]
	v_pk_fma_f32 v[58:59], v[58:59], v[236:237], v[62:63]
	v_pk_fma_f32 v[60:61], v[60:61], v[238:239], v[64:65]
	v_cvt_pk_bf16_f32 v62, v130, v131
	v_cvt_pk_bf16_f32 v63, v132, v133
	v_cvt_pk_bf16_f32 v64, v58, v59
	v_cvt_pk_bf16_f32 v65, v60, v61
	v_lshl_add_u64 v[132:133], v[170:171], 0, v[212:213]
	global_store_dwordx4 v[132:133], v[62:65], off
	v_pk_mul_f32 v[130:131], v[50:51], v[240:241]
	v_pk_mul_f32 v[132:133], v[52:53], v[242:243]
	v_pk_fma_f32 v[130:131], v[54:55], v[236:237], v[130:131] neg_lo:[0,0,1] neg_hi:[0,0,1]
	v_pk_fma_f32 v[132:133], v[56:57], v[238:239], v[132:133] neg_lo:[0,0,1] neg_hi:[0,0,1]
	v_pk_mul_f32 v[54:55], v[54:55], v[240:241]
	v_pk_mul_f32 v[56:57], v[56:57], v[242:243]
	v_pk_fma_f32 v[50:51], v[50:51], v[236:237], v[54:55]
	v_pk_fma_f32 v[52:53], v[52:53], v[238:239], v[56:57]
	v_cvt_pk_bf16_f32 v54, v130, v131
	v_cvt_pk_bf16_f32 v55, v132, v133
	v_cvt_pk_bf16_f32 v56, v50, v51
	v_cvt_pk_bf16_f32 v57, v52, v53
	v_lshl_add_u64 v[132:133], v[134:135], 0, v[212:213]
	global_store_dwordx4 v[132:133], v[54:57], off
	v_or_b32_e32 v145, 0x90, v202
	v_mul_lo_u32 v0, s57, v145
	v_mad_u64_u32 v[212:213], s[2:3], s56, v145, 0
	v_add3_u32 v213, v213, v203, v0
	v_lshlrev_b64 v[212:213], 1, v[212:213]
	s_waitcnt vmcnt(14)
	v_pk_mul_f32 v[174:175], v[144:145], v[174:175] op_sel_hi:[0,1]
	v_pk_mul_f32 v[176:177], v[144:145], v[176:177] op_sel_hi:[0,1]
	v_pk_mul_f32 v[204:205], v[144:145], v[204:205] op_sel_hi:[0,1]
	v_pk_mul_f32 v[206:207], v[144:145], v[206:207] op_sel_hi:[0,1]
	v_pk_mul_f32 v[130:131], v[42:43], v[204:205]
	v_pk_mul_f32 v[132:133], v[44:45], v[206:207]
	v_pk_fma_f32 v[130:131], v[46:47], v[174:175], v[130:131] neg_lo:[0,0,1] neg_hi:[0,0,1]
	v_pk_fma_f32 v[132:133], v[48:49], v[176:177], v[132:133] neg_lo:[0,0,1] neg_hi:[0,0,1]
	v_pk_mul_f32 v[46:47], v[46:47], v[204:205]
	v_pk_mul_f32 v[48:49], v[48:49], v[206:207]
	v_pk_fma_f32 v[42:43], v[42:43], v[174:175], v[46:47]
	v_pk_fma_f32 v[44:45], v[44:45], v[176:177], v[48:49]
	v_cvt_pk_bf16_f32 v46, v130, v131
	v_cvt_pk_bf16_f32 v47, v132, v133
	v_cvt_pk_bf16_f32 v48, v42, v43
	v_cvt_pk_bf16_f32 v49, v44, v45
	v_lshl_add_u64 v[132:133], v[170:171], 0, v[212:213]
	global_store_dwordx4 v[132:133], v[46:49], off
	v_pk_mul_f32 v[130:131], v[34:35], v[204:205]
	v_pk_mul_f32 v[132:133], v[36:37], v[206:207]
	v_pk_fma_f32 v[130:131], v[38:39], v[174:175], v[130:131] neg_lo:[0,0,1] neg_hi:[0,0,1]
	v_pk_fma_f32 v[132:133], v[40:41], v[176:177], v[132:133] neg_lo:[0,0,1] neg_hi:[0,0,1]
	v_pk_mul_f32 v[38:39], v[38:39], v[204:205]
	v_pk_mul_f32 v[40:41], v[40:41], v[206:207]
	v_pk_fma_f32 v[34:35], v[34:35], v[174:175], v[38:39]
	v_pk_fma_f32 v[36:37], v[36:37], v[176:177], v[40:41]
	v_cvt_pk_bf16_f32 v38, v130, v131
	v_cvt_pk_bf16_f32 v39, v132, v133
	v_cvt_pk_bf16_f32 v40, v34, v35
	v_cvt_pk_bf16_f32 v41, v36, v37
	v_lshl_add_u64 v[132:133], v[134:135], 0, v[212:213]
	global_store_dwordx4 v[132:133], v[38:41], off
	v_or_b32_e32 v145, 0xa0, v202
	v_mul_lo_u32 v0, s57, v145
	v_mad_u64_u32 v[212:213], s[2:3], s56, v145, 0
	v_add3_u32 v213, v213, v203, v0
	v_lshlrev_b64 v[212:213], 1, v[212:213]
	s_waitcnt vmcnt(12)
	v_pk_mul_f32 v[136:137], v[144:145], v[136:137] op_sel_hi:[0,1]
	v_pk_mul_f32 v[138:139], v[144:145], v[138:139] op_sel_hi:[0,1]
	v_pk_mul_f32 v[140:141], v[144:145], v[140:141] op_sel_hi:[0,1]
	v_pk_mul_f32 v[142:143], v[144:145], v[142:143] op_sel_hi:[0,1]
	v_pk_mul_f32 v[130:131], v[26:27], v[140:141]
	v_pk_mul_f32 v[132:133], v[28:29], v[142:143]
	v_pk_fma_f32 v[130:131], v[30:31], v[136:137], v[130:131] neg_lo:[0,0,1] neg_hi:[0,0,1]
	v_pk_fma_f32 v[132:133], v[32:33], v[138:139], v[132:133] neg_lo:[0,0,1] neg_hi:[0,0,1]
	v_pk_mul_f32 v[30:31], v[30:31], v[140:141]
	v_pk_mul_f32 v[32:33], v[32:33], v[142:143]
	v_pk_fma_f32 v[26:27], v[26:27], v[136:137], v[30:31]
	v_pk_fma_f32 v[28:29], v[28:29], v[138:139], v[32:33]
	v_cvt_pk_bf16_f32 v30, v130, v131
	v_cvt_pk_bf16_f32 v31, v132, v133
	v_cvt_pk_bf16_f32 v32, v26, v27
	v_cvt_pk_bf16_f32 v33, v28, v29
	v_lshl_add_u64 v[132:133], v[170:171], 0, v[212:213]
	global_store_dwordx4 v[132:133], v[30:33], off
	v_pk_mul_f32 v[130:131], v[18:19], v[140:141]
	v_pk_mul_f32 v[132:133], v[20:21], v[142:143]
	v_pk_fma_f32 v[130:131], v[22:23], v[136:137], v[130:131] neg_lo:[0,0,1] neg_hi:[0,0,1]
	v_pk_fma_f32 v[132:133], v[24:25], v[138:139], v[132:133] neg_lo:[0,0,1] neg_hi:[0,0,1]
	v_pk_mul_f32 v[22:23], v[22:23], v[140:141]
	v_pk_mul_f32 v[24:25], v[24:25], v[142:143]
	v_pk_fma_f32 v[18:19], v[18:19], v[136:137], v[22:23]
	v_pk_fma_f32 v[20:21], v[20:21], v[138:139], v[24:25]
	v_cvt_pk_bf16_f32 v22, v130, v131
	v_cvt_pk_bf16_f32 v23, v132, v133
	v_cvt_pk_bf16_f32 v24, v18, v19
	v_cvt_pk_bf16_f32 v25, v20, v21
	v_lshl_add_u64 v[132:133], v[134:135], 0, v[212:213]
	global_store_dwordx4 v[132:133], v[22:25], off
	v_or_b32_e32 v145, 0xb0, v202
	v_mul_lo_u32 v0, s57, v145
	v_mad_u64_u32 v[176:177], s[2:3], s56, v145, 0
	v_add3_u32 v177, v177, v203, v0
	v_lshlrev_b64 v[212:213], 1, v[176:177]
	s_waitcnt vmcnt(10)
	v_pk_mul_f32 v[208:209], v[144:145], v[208:209] op_sel_hi:[0,1]
	v_pk_mul_f32 v[210:211], v[144:145], v[210:211] op_sel_hi:[0,1]
	v_pk_mul_f32 v[216:217], v[144:145], v[216:217] op_sel_hi:[0,1]
	v_pk_mul_f32 v[218:219], v[144:145], v[218:219] op_sel_hi:[0,1]
	v_pk_mul_f32 v[130:131], v[10:11], v[216:217]
	v_pk_mul_f32 v[132:133], v[12:13], v[218:219]
	v_pk_fma_f32 v[130:131], v[14:15], v[208:209], v[130:131] neg_lo:[0,0,1] neg_hi:[0,0,1]
	v_pk_fma_f32 v[132:133], v[16:17], v[210:211], v[132:133] neg_lo:[0,0,1] neg_hi:[0,0,1]
	v_pk_mul_f32 v[14:15], v[14:15], v[216:217]
	v_pk_mul_f32 v[16:17], v[16:17], v[218:219]
	v_pk_fma_f32 v[10:11], v[10:11], v[208:209], v[14:15]
	v_pk_fma_f32 v[12:13], v[12:13], v[210:211], v[16:17]
	v_cvt_pk_bf16_f32 v14, v130, v131
	v_cvt_pk_bf16_f32 v15, v132, v133
	v_cvt_pk_bf16_f32 v16, v10, v11
	v_cvt_pk_bf16_f32 v17, v12, v13
	v_lshl_add_u64 v[132:133], v[170:171], 0, v[212:213]
	global_store_dwordx4 v[132:133], v[14:17], off
	v_pk_mul_f32 v[130:131], v[2:3], v[216:217]
	v_pk_mul_f32 v[132:133], v[4:5], v[218:219]
	v_pk_fma_f32 v[130:131], v[6:7], v[208:209], v[130:131] neg_lo:[0,0,1] neg_hi:[0,0,1]
	v_pk_fma_f32 v[132:133], v[8:9], v[210:211], v[132:133] neg_lo:[0,0,1] neg_hi:[0,0,1]
	v_pk_mul_f32 v[6:7], v[6:7], v[216:217]
	v_pk_mul_f32 v[8:9], v[8:9], v[218:219]
	v_pk_fma_f32 v[2:3], v[2:3], v[208:209], v[6:7]
	v_pk_fma_f32 v[4:5], v[4:5], v[210:211], v[8:9]
	v_cvt_pk_bf16_f32 v130, v130, v131
	v_cvt_pk_bf16_f32 v131, v132, v133
	v_cvt_pk_bf16_f32 v132, v2, v3
	v_mov_b32_e32 v136, v4
	v_mov_b32_e32 v137, v5
